# GLA waves also commit the next chunk inside their block (before transposes stage 2); common commit removed
# speedup vs baseline: 1.0012x; 1.0012x over previous
; #define LAS __attribute__((address_space(3)))
; #define LO2(v4) (__builtin_shufflevector(v4, v4, 0, 1))
; #define HI2(v4) (__builtin_shufflevector(v4, v4, 2, 3))
; __device__ __forceinline__ f32x2 fma2(f32x2 a, f32x2 b, f32x2 c) { return __builtin_elementwise_fma(a, b, c); }
; #define GLA_LOAD(d, s) do { const LAS float* p_ = bg + (s) * SCG; d.q = *(const LAS f32x4*)(p_); d.k = *(const LAS f32x4*)(p_ + 64); d.u = *(const LAS f32x4*)(p_ + 256); d.v = bv[(s) * SCG]; } while (0)
; __device__ __forceinline__ void scan_phase(const Args& a, int e, LAS unsigned char* lds) {
;     ...
;             } else {
;                 const LAS float* bg = bufG + bi * TC * SCG + 4 * g; const LAS float* bv = bufG + bi * TC * SCG + 128 + vrow;
;     ...
;                 GlaIn in[3];
;                 GLA_LOAD(in[0], 0); GLA_LOAD(in[1], 1);
; #pragma unroll
;                 for (int s = 0; s < TC; ++s) {
;                     if (s + 2 < TC) GLA_LOAD(in[(s + 2) % 3], s + 2);
;                     __builtin_amdgcn_sched_barrier(0);
;                     const GlaIn& x = in[s % 3];
;                     const f32x2 vv = {x.v, x.v};
;                     P0 = fma2(vv, LO2(x.k), fma2(-LO2(x.u), P0, P0)); P1 = fma2(vv, HI2(x.k), fma2(-HI2(x.u), P1, P1));
;                     const f32x2 o2 = fma2(P1, HI2(x.q), P0 * LO2(x.q));
;                     op[s] = o2.x + o2.y;
;                 }
.LBB0_237:
	s_and_b32 s14, s14, 1
	s_and_saveexec_b64 s[12:13], s[40:41]
	s_xor_b64 s[12:13], exec, s[12:13]
	s_cbranch_execz .LBB0_239
	s_mul_i32 s15, s14, 0x5000
	v_or_b32_e32 v43, s15, v55
	v_lshl_or_b32 v45, v77, 2, s15
	ds_read_b128 v[48:51], v43 offset:49152
	ds_read_b128 v[78:81], v43 offset:49408
	ds_read2st64_b32 v[24:25], v45 offset0:194 offset1:199
	ds_read_b128 v[82:85], v43 offset:50176
	ds_read_b128 v[86:89], v43 offset:50432
	ds_read_b128 v[90:93], v43 offset:50688
	ds_read_b128 v[94:97], v43 offset:51456
	ds_read_b128 v[98:101], v43 offset:51712
	ds_read_b128 v[102:105], v43 offset:51968
	ds_read_b128 v[106:109], v43 offset:52736
	ds_read_b32 v110, v45 offset:52224
	v_add_u32_e32 v22, 0xc000, v43
	v_add_u32_e32 v23, 0xc200, v45
	s_waitcnt lgkmcnt(7)
	v_xor_b32_e32 v85, 0x80000000, v85
	v_xor_b32_e32 v84, 0x80000000, v84
	v_pk_fma_f32 v[14:15], v[82:83], v[14:15], v[14:15] neg_lo:[1,0,0] neg_hi:[1,0,0]
	s_nop 0
	v_pk_fma_f32 v[82:83], v[24:25], v[78:79], v[14:15] op_sel_hi:[0,1,1]
	v_pk_fma_f32 v[14:15], v[84:85], v[16:17], v[16:17]
	s_nop 0
	v_pk_fma_f32 v[84:85], v[24:25], v[80:81], v[14:15] op_sel_hi:[0,1,1]
	v_pk_mul_f32 v[14:15], v[48:49], v[82:83]
	s_nop 0
	v_pk_fma_f32 v[14:15], v[84:85], v[50:51], v[14:15]
	s_nop 0
	v_add_f32_e32 v19, v14, v15
	ds_read_b128 v[14:17], v43 offset:52992
	ds_read_b128 v[48:51], v43 offset:53248
	ds_read_b128 v[78:81], v43 offset:54016
	ds_read_b32 v112, v45 offset:53504
	v_mov_b32_e32 v24, v25
	s_waitcnt lgkmcnt(8)
	v_xor_b32_e32 v97, 0x80000000, v97
	v_xor_b32_e32 v96, 0x80000000, v96
	v_pk_fma_f32 v[82:83], v[94:95], v[82:83], v[82:83] neg_lo:[1,0,0] neg_hi:[1,0,0]
	s_nop 0
	v_pk_fma_f32 v[94:95], v[24:25], v[90:91], v[82:83] op_sel_hi:[0,1,1]
	v_pk_fma_f32 v[82:83], v[96:97], v[84:85], v[84:85]
	s_nop 0
	v_pk_fma_f32 v[24:25], v[24:25], v[92:93], v[82:83] op_sel_hi:[0,1,1]
	v_pk_mul_f32 v[82:83], v[86:87], v[94:95]
	s_nop 0
	v_pk_fma_f32 v[82:83], v[24:25], v[88:89], v[82:83]
	s_nop 0
	v_add_f32_e32 v21, v82, v83
	ds_read_b128 v[82:85], v43 offset:54272
	ds_read_b128 v[86:89], v43 offset:54528
	ds_read_b128 v[90:93], v43 offset:55296
	ds_read_b32 v114, v45 offset:54784
	s_waitcnt lgkmcnt(9)
	v_xor_b32_e32 v97, 0x80000000, v109
	v_xor_b32_e32 v96, 0x80000000, v108
	v_pk_fma_f32 v[94:95], v[106:107], v[94:95], v[94:95] neg_lo:[1,0,0] neg_hi:[1,0,0]
	v_pk_fma_f32 v[24:25], v[96:97], v[24:25], v[24:25]
	s_waitcnt lgkmcnt(8)
	v_pk_fma_f32 v[106:107], v[110:111], v[102:103], v[94:95] op_sel_hi:[0,1,1]
	v_pk_fma_f32 v[108:109], v[110:111], v[104:105], v[24:25] op_sel_hi:[0,1,1]
	v_pk_mul_f32 v[24:25], v[98:99], v[106:107]
	s_nop 0
	v_pk_fma_f32 v[24:25], v[108:109], v[100:101], v[24:25]
	ds_read_b128 v[94:97], v43 offset:55552
	ds_read_b128 v[98:101], v43 offset:55808
	ds_read_b128 v[102:105], v43 offset:56576
	ds_read_b32 v110, v45 offset:56064
	v_add_f32_e32 v24, v24, v25
	s_waitcnt lgkmcnt(9)
	v_xor_b32_e32 v81, 0x80000000, v81
	v_xor_b32_e32 v80, 0x80000000, v80
	v_pk_fma_f32 v[78:79], v[78:79], v[106:107], v[106:107] neg_lo:[1,0,0] neg_hi:[1,0,0]
	s_waitcnt lgkmcnt(8)
	v_pk_fma_f32 v[106:107], v[112:113], v[48:49], v[78:79] op_sel_hi:[0,1,1]
	v_pk_fma_f32 v[48:49], v[80:81], v[108:109], v[108:109]
	v_pk_mul_f32 v[14:15], v[14:15], v[106:107]
	v_pk_fma_f32 v[108:109], v[112:113], v[50:51], v[48:49] op_sel_hi:[0,1,1]
	v_pk_fma_f32 v[14:15], v[108:109], v[16:17], v[14:15]
	s_nop 0
	v_add_f32_e32 v25, v14, v15
	ds_read_b128 v[14:17], v43 offset:56832
	ds_read_b128 v[48:51], v43 offset:57088
	ds_read_b128 v[78:81], v43 offset:57856
	ds_read_b32 v112, v45 offset:57344
	s_waitcnt lgkmcnt(9)
	v_xor_b32_e32 v93, 0x80000000, v93
	v_xor_b32_e32 v92, 0x80000000, v92
	v_pk_fma_f32 v[90:91], v[90:91], v[106:107], v[106:107] neg_lo:[1,0,0] neg_hi:[1,0,0]
	s_waitcnt lgkmcnt(8)
	v_pk_fma_f32 v[106:107], v[114:115], v[86:87], v[90:91] op_sel_hi:[0,1,1]
	v_pk_fma_f32 v[86:87], v[92:93], v[108:109], v[108:109]
	v_pk_mul_f32 v[82:83], v[82:83], v[106:107]
	v_pk_fma_f32 v[108:109], v[114:115], v[88:89], v[86:87] op_sel_hi:[0,1,1]
	v_pk_fma_f32 v[82:83], v[108:109], v[84:85], v[82:83]
	s_nop 0
	v_add_f32_e32 v111, v82, v83
	ds_read_b128 v[82:85], v43 offset:58112
	ds_read_b128 v[86:89], v43 offset:58368
	ds_read_b128 v[90:93], v43 offset:59136
	ds_read_b32 v114, v45 offset:58624
	s_waitcnt lgkmcnt(9)
	v_xor_b32_e32 v105, 0x80000000, v105
	v_xor_b32_e32 v104, 0x80000000, v104
	v_pk_fma_f32 v[102:103], v[102:103], v[106:107], v[106:107] neg_lo:[1,0,0] neg_hi:[1,0,0]
	s_waitcnt lgkmcnt(8)
	v_pk_fma_f32 v[106:107], v[110:111], v[98:99], v[102:103] op_sel_hi:[0,1,1]
	v_pk_fma_f32 v[98:99], v[104:105], v[108:109], v[108:109]
	v_pk_mul_f32 v[94:95], v[94:95], v[106:107]
	v_pk_fma_f32 v[108:109], v[110:111], v[100:101], v[98:99] op_sel_hi:[0,1,1]
	v_pk_fma_f32 v[94:95], v[108:109], v[96:97], v[94:95]
	s_nop 0
	v_add_f32_e32 v113, v94, v95
	ds_read_b128 v[94:97], v43 offset:59392
	ds_read_b128 v[98:101], v43 offset:59648
	ds_read_b128 v[102:105], v43 offset:60416
	ds_read_b32 v110, v45 offset:59904
	s_waitcnt lgkmcnt(9)
	v_xor_b32_e32 v81, 0x80000000, v81
	v_xor_b32_e32 v80, 0x80000000, v80
	v_pk_fma_f32 v[78:79], v[78:79], v[106:107], v[106:107] neg_lo:[1,0,0] neg_hi:[1,0,0]
	s_waitcnt lgkmcnt(8)
	v_pk_fma_f32 v[106:107], v[112:113], v[48:49], v[78:79] op_sel_hi:[0,1,1]
	v_pk_fma_f32 v[48:49], v[80:81], v[108:109], v[108:109]
	v_pk_mul_f32 v[14:15], v[14:15], v[106:107]
	v_pk_fma_f32 v[108:109], v[112:113], v[50:51], v[48:49] op_sel_hi:[0,1,1]
	v_pk_fma_f32 v[14:15], v[108:109], v[16:17], v[14:15]
	s_nop 0
	v_add_f32_e32 v115, v14, v15
	ds_read_b128 v[14:17], v43 offset:60672
	ds_read_b128 v[48:51], v43 offset:60928
	ds_read_b128 v[78:81], v43 offset:61696
	ds_read_b32 v112, v45 offset:61184
	s_waitcnt lgkmcnt(9)
; #define LO2(v4) (__builtin_shufflevector(v4, v4, 0, 1))
; #define HI2(v4) (__builtin_shufflevector(v4, v4, 2, 3))
; __device__ __forceinline__ f32x2 fma2(f32x2 a, f32x2 b, f32x2 c) { return __builtin_elementwise_fma(a, b, c); }
; #define GLA_LOAD(d, s) do { const LAS float* p_ = bg + (s) * SCG; d.q = *(const LAS f32x4*)(p_); d.k = *(const LAS f32x4*)(p_ + 64); d.u = *(const LAS f32x4*)(p_ + 256); d.v = bv[(s) * SCG]; } while (0)
; __device__ __forceinline__ void scan_phase(const Args& a, int e, LAS unsigned char* lds) {
;     ...
;                 GLA_LOAD(in[0], 0); GLA_LOAD(in[1], 1);
; #pragma unroll
;                 for (int s = 0; s < TC; ++s) {
;                     if (s + 2 < TC) GLA_LOAD(in[(s + 2) % 3], s + 2);
;                     __builtin_amdgcn_sched_barrier(0);
;                     const GlaIn& x = in[s % 3];
;                     const f32x2 vv = {x.v, x.v};
;                     P0 = fma2(vv, LO2(x.k), fma2(-LO2(x.u), P0, P0)); P1 = fma2(vv, HI2(x.k), fma2(-HI2(x.u), P1, P1));
;                     const f32x2 o2 = fma2(P1, HI2(x.q), P0 * LO2(x.q));
;                     op[s] = o2.x + o2.y;
;                 }
	v_xor_b32_e32 v93, 0x80000000, v93
	v_xor_b32_e32 v92, 0x80000000, v92
	v_pk_fma_f32 v[90:91], v[90:91], v[106:107], v[106:107] neg_lo:[1,0,0] neg_hi:[1,0,0]
	s_waitcnt lgkmcnt(8)
	v_pk_fma_f32 v[106:107], v[114:115], v[86:87], v[90:91] op_sel_hi:[0,1,1]
	v_pk_fma_f32 v[86:87], v[92:93], v[108:109], v[108:109]
	v_pk_mul_f32 v[82:83], v[82:83], v[106:107]
	v_pk_fma_f32 v[108:109], v[114:115], v[88:89], v[86:87] op_sel_hi:[0,1,1]
	v_pk_fma_f32 v[82:83], v[108:109], v[84:85], v[82:83]
	s_nop 0
	v_add_f32_e32 v116, v82, v83
	ds_read_b128 v[82:85], v43 offset:61952
	ds_read_b128 v[86:89], v43 offset:62208
	ds_read_b128 v[90:93], v43 offset:62976
	ds_read_b32 v114, v45 offset:62464
	s_waitcnt lgkmcnt(9)
	v_xor_b32_e32 v105, 0x80000000, v105
	v_xor_b32_e32 v104, 0x80000000, v104
	v_pk_fma_f32 v[102:103], v[102:103], v[106:107], v[106:107] neg_lo:[1,0,0] neg_hi:[1,0,0]
	s_waitcnt lgkmcnt(8)
	v_pk_fma_f32 v[106:107], v[110:111], v[98:99], v[102:103] op_sel_hi:[0,1,1]
	v_pk_fma_f32 v[98:99], v[104:105], v[108:109], v[108:109]
	v_pk_mul_f32 v[94:95], v[94:95], v[106:107]
	v_pk_fma_f32 v[108:109], v[110:111], v[100:101], v[98:99] op_sel_hi:[0,1,1]
	v_pk_fma_f32 v[94:95], v[108:109], v[96:97], v[94:95]
	s_nop 0
	v_add_f32_e32 v117, v94, v95
	ds_read_b128 v[94:97], v43 offset:63232
	ds_read_b128 v[98:101], v43 offset:63488
	ds_read_b128 v[102:105], v43 offset:64256
	ds_read_b32 v110, v45 offset:63744
	s_waitcnt lgkmcnt(9)
	v_xor_b32_e32 v81, 0x80000000, v81
	v_xor_b32_e32 v80, 0x80000000, v80
	v_pk_fma_f32 v[78:79], v[78:79], v[106:107], v[106:107] neg_lo:[1,0,0] neg_hi:[1,0,0]
	s_waitcnt lgkmcnt(8)
	v_pk_fma_f32 v[106:107], v[112:113], v[48:49], v[78:79] op_sel_hi:[0,1,1]
	v_pk_fma_f32 v[48:49], v[80:81], v[108:109], v[108:109]
	v_pk_mul_f32 v[14:15], v[14:15], v[106:107]
	v_pk_fma_f32 v[108:109], v[112:113], v[50:51], v[48:49] op_sel_hi:[0,1,1]
	v_pk_fma_f32 v[14:15], v[108:109], v[16:17], v[14:15]
	s_nop 0
	v_add_f32_e32 v118, v14, v15
	ds_read_b128 v[14:17], v43 offset:64512
	ds_read_b128 v[48:51], v43 offset:64768
	ds_read_b128 v[78:81], v22 offset:16384
	ds_read_b32 v112, v45 offset:65024
	s_waitcnt lgkmcnt(9)
	v_xor_b32_e32 v93, 0x80000000, v93
	v_xor_b32_e32 v92, 0x80000000, v92
	v_pk_fma_f32 v[90:91], v[90:91], v[106:107], v[106:107] neg_lo:[1,0,0] neg_hi:[1,0,0]
	s_waitcnt lgkmcnt(8)
	v_pk_fma_f32 v[106:107], v[114:115], v[86:87], v[90:91] op_sel_hi:[0,1,1]
	v_pk_fma_f32 v[86:87], v[92:93], v[108:109], v[108:109]
	v_pk_mul_f32 v[82:83], v[82:83], v[106:107]
	v_pk_fma_f32 v[108:109], v[114:115], v[88:89], v[86:87] op_sel_hi:[0,1,1]
	v_pk_fma_f32 v[82:83], v[108:109], v[84:85], v[82:83]
	s_nop 0
	v_add_f32_e32 v43, v82, v83
	ds_read_b128 v[82:85], v22 offset:16640
	ds_read_b128 v[86:89], v22 offset:16896
	ds_read_b128 v[90:93], v22 offset:17664
	ds_read_b32 v114, v23 offset:16640
	s_waitcnt lgkmcnt(9)
	v_xor_b32_e32 v105, 0x80000000, v105
	v_xor_b32_e32 v104, 0x80000000, v104
	v_pk_fma_f32 v[102:103], v[102:103], v[106:107], v[106:107] neg_lo:[1,0,0] neg_hi:[1,0,0]
	s_waitcnt lgkmcnt(8)
	v_pk_fma_f32 v[106:107], v[110:111], v[98:99], v[102:103] op_sel_hi:[0,1,1]
	v_pk_fma_f32 v[98:99], v[104:105], v[108:109], v[108:109]
	v_pk_mul_f32 v[94:95], v[94:95], v[106:107]
	v_pk_fma_f32 v[108:109], v[110:111], v[100:101], v[98:99] op_sel_hi:[0,1,1]
	v_pk_fma_f32 v[94:95], v[108:109], v[96:97], v[94:95]
	s_nop 0
	v_add_f32_e32 v45, v94, v95
	ds_read_b128 v[94:97], v22 offset:17920
	ds_read_b128 v[98:101], v22 offset:18176
	ds_read_b128 v[102:105], v22 offset:18944
	ds_read_b32 v110, v23 offset:17920
	s_waitcnt lgkmcnt(9)
	v_xor_b32_e32 v81, 0x80000000, v81
	v_xor_b32_e32 v80, 0x80000000, v80
	v_pk_fma_f32 v[78:79], v[78:79], v[106:107], v[106:107] neg_lo:[1,0,0] neg_hi:[1,0,0]
	s_waitcnt lgkmcnt(8)
	v_pk_fma_f32 v[106:107], v[112:113], v[48:49], v[78:79] op_sel_hi:[0,1,1]
	v_pk_fma_f32 v[48:49], v[80:81], v[108:109], v[108:109]
	v_pk_mul_f32 v[14:15], v[14:15], v[106:107]
	v_pk_fma_f32 v[108:109], v[112:113], v[50:51], v[48:49] op_sel_hi:[0,1,1]
	v_pk_fma_f32 v[14:15], v[108:109], v[16:17], v[14:15]
	s_nop 0
	v_add_f32_e32 v112, v14, v15
	ds_read_b128 v[48:51], v22 offset:19200
	ds_read_b128 v[14:17], v22 offset:19456
	ds_read_b128 v[78:81], v22 offset:20224
	ds_read_b32 v22, v23 offset:19200
	s_waitcnt lgkmcnt(9)
	v_xor_b32_e32 v93, 0x80000000, v93
	v_xor_b32_e32 v92, 0x80000000, v92
	v_pk_fma_f32 v[90:91], v[90:91], v[106:107], v[106:107] neg_lo:[1,0,0] neg_hi:[1,0,0]
	s_waitcnt lgkmcnt(8)
	v_pk_fma_f32 v[86:87], v[114:115], v[86:87], v[90:91] op_sel_hi:[0,1,1]
	v_pk_fma_f32 v[90:91], v[92:93], v[108:109], v[108:109]
	v_pk_mul_f32 v[82:83], v[82:83], v[86:87]
	v_pk_fma_f32 v[88:89], v[114:115], v[88:89], v[90:91] op_sel_hi:[0,1,1]
	v_pk_fma_f32 v[82:83], v[88:89], v[84:85], v[82:83]
	s_nop 0
	v_add_f32_e32 v90, v82, v83
	s_waitcnt lgkmcnt(5)
	v_xor_b32_e32 v83, 0x80000000, v105
	v_xor_b32_e32 v82, 0x80000000, v104
	v_pk_fma_f32 v[84:85], v[102:103], v[86:87], v[86:87] neg_lo:[1,0,0] neg_hi:[1,0,0]
	v_pk_fma_f32 v[82:83], v[82:83], v[88:89], v[88:89]
	s_waitcnt lgkmcnt(4)
; #define TR_DPP(x, ctrl) __builtin_bit_cast(float, __builtin_amdgcn_update_dpp(0, __builtin_bit_cast(int, x), ctrl, 0xf, 0xf, false))
; __device__ __forceinline__ float transpose_reduce16(const float* p, int g) {
;     const bool h1 = (g & 8) != 0, h2 = (g & 4) != 0, h3 = (g & 2) != 0, h4 = (g & 1) != 0;
;     float q[8], r[4], t[2];
; #pragma unroll
;     for (int i = 0; i < 8; ++i) { const float keep = h1 ? p[i + 8] : p[i], send = h1 ? p[i] : p[i + 8]; q[i] = keep + TR_DPP(send, 0x140); }
; #pragma unroll
;     for (int i = 0; i < 4; ++i) { const float keep = h2 ? q[i + 4] : q[i], send = h2 ? q[i] : q[i + 4]; r[i] = keep + TR_DPP(send, 0x141); }
; #pragma unroll
;     for (int i = 0; i < 2; ++i) { const float keep = h3 ? r[i + 2] : r[i], send = h3 ? r[i] : r[i + 2]; t[i] = keep + TR_DPP(send, 0x4E); }
;     const float keep = h4 ? t[1] : t[0], send = h4 ? t[0] : t[1];
;     return keep + TR_DPP(send, 0xB1);
	v_pk_fma_f32 v[84:85], v[110:111], v[98:99], v[84:85] op_sel_hi:[0,1,1]
	v_pk_fma_f32 v[82:83], v[110:111], v[100:101], v[82:83] op_sel_hi:[0,1,1]
	v_pk_mul_f32 v[86:87], v[94:95], v[84:85]
	s_nop 0
	v_pk_fma_f32 v[86:87], v[82:83], v[96:97], v[86:87]
	s_nop 0
	v_add_f32_e32 v86, v86, v87
	s_waitcnt lgkmcnt(1)
	v_xor_b32_e32 v81, 0x80000000, v81
	v_xor_b32_e32 v80, 0x80000000, v80
	v_pk_fma_f32 v[78:79], v[78:79], v[84:85], v[84:85] neg_lo:[1,0,0] neg_hi:[1,0,0]
	s_waitcnt lgkmcnt(0)
	v_pk_fma_f32 v[14:15], v[22:23], v[14:15], v[78:79] op_sel_hi:[0,1,1]
	v_pk_fma_f32 v[78:79], v[80:81], v[82:83], v[82:83]
	s_nop 0
	v_pk_fma_f32 v[16:17], v[22:23], v[16:17], v[78:79] op_sel_hi:[0,1,1]
	v_pk_mul_f32 v[22:23], v[48:49], v[14:15]
	v_cndmask_b32_e64 v48, v115, v86, s[42:43]
	v_pk_fma_f32 v[22:23], v[16:17], v[50:51], v[22:23]
	s_nop 0
	v_add_f32_e32 v22, v22, v23
	v_cndmask_b32_e64 v23, v117, v19, s[42:43]
	v_cndmask_b32_e64 v19, v19, v117, s[42:43]
	s_nop 1
	v_add_f32_dpp v19, v19, v23 row_mirror row_mask:0xf bank_mask:0xf bound_ctrl:1
	v_cndmask_b32_e64 v23, v118, v21, s[42:43]
	v_cndmask_b32_e64 v21, v21, v118, s[42:43]
	s_nop 1
	v_add_f32_dpp v21, v21, v23 row_mirror row_mask:0xf bank_mask:0xf bound_ctrl:1
	v_cndmask_b32_e64 v23, v43, v24, s[42:43]
	v_cndmask_b32_e64 v24, v24, v43, s[42:43]
	v_cndmask_b32_e64 v43, v111, v112, s[42:43]
	s_nop 0
	v_add_f32_dpp v23, v24, v23 row_mirror row_mask:0xf bank_mask:0xf bound_ctrl:1
	v_cndmask_b32_e64 v24, v45, v25, s[42:43]
	v_cndmask_b32_e64 v25, v25, v45, s[42:43]
	v_cndmask_b32_e64 v45, v113, v90, s[42:43]
	s_nop 0
	v_add_f32_dpp v24, v25, v24 row_mirror row_mask:0xf bank_mask:0xf bound_ctrl:1
	v_cndmask_b32_e64 v25, v112, v111, s[42:43]
	s_nop 1
	v_add_f32_dpp v25, v43, v25 row_mirror row_mask:0xf bank_mask:0xf bound_ctrl:1
	v_cndmask_b32_e64 v43, v90, v113, s[42:43]
	s_nop 1
	v_add_f32_dpp v43, v45, v43 row_mirror row_mask:0xf bank_mask:0xf bound_ctrl:1
	v_cndmask_b32_e64 v45, v86, v115, s[42:43]
	s_nop 1
	v_add_f32_dpp v45, v48, v45 row_mirror row_mask:0xf bank_mask:0xf bound_ctrl:1
	v_cndmask_b32_e64 v48, v22, v116, s[42:43]
	v_cndmask_b32_e64 v22, v116, v22, s[42:43]
	s_nop 1
	v_add_f32_dpp v22, v22, v48 row_mirror row_mask:0xf bank_mask:0xf bound_ctrl:1
	s_lshl_b32 s15, s14, 4
	s_xor_b32 s15, s15, 16
	v_or_b32_e32 v78, s15, v54
	v_add_u32_e32 v79, s15, v53
	v_mad_u32_u24 v78, v78, v67, v68
	v_mad_u32_u24 v79, v79, v67, v69
	s_waitcnt vmcnt(0)
	v_lshlrev_b32_e32 v82, 16, v6
	v_and_b32_e32 v83, 0xffff0000, v6
	v_lshlrev_b32_e32 v84, 16, v7
	v_and_b32_e32 v85, 0xffff0000, v7
	v_lshlrev_b32_e32 v86, 16, v8
	v_and_b32_e32 v87, 0xffff0000, v8
	v_lshlrev_b32_e32 v88, 16, v9
	v_and_b32_e32 v89, 0xffff0000, v9
	v_lshlrev_b32_e32 v92, 16, v10
	v_and_b32_e32 v93, 0xffff0000, v10
	v_lshlrev_b32_e32 v94, 16, v11
	v_and_b32_e32 v95, 0xffff0000, v11
	v_lshlrev_b32_e32 v96, 16, v12
	v_and_b32_e32 v97, 0xffff0000, v12
	v_lshlrev_b32_e32 v98, 16, v13
	v_and_b32_e32 v99, 0xffff0000, v13
	ds_write_b128 v78, v[82:85]
	ds_write_b128 v78, v[86:89] offset:16
	ds_write_b128 v79, v[92:95]
	ds_write_b128 v79, v[96:99] offset:16
	s_cmp_eq_u64 s[0:1], 0
	s_cbranch_scc1 .Lgla_no_piece2
	v_add_u32_e32 v80, s15, v31
	v_mad_u32_u24 v80, v80, v67, v70
	v_lshlrev_b32_e32 v100, 16, v2
	v_and_b32_e32 v101, 0xffff0000, v2
	v_lshlrev_b32_e32 v102, 16, v3
	v_and_b32_e32 v103, 0xffff0000, v3
	v_lshlrev_b32_e32 v104, 16, v4
	v_and_b32_e32 v105, 0xffff0000, v4
	v_lshlrev_b32_e32 v106, 16, v5
	v_and_b32_e32 v107, 0xffff0000, v5
	ds_write_b128 v80, v[100:103]
	ds_write_b128 v80, v[104:107] offset:16
.Lgla_no_piece2:
	v_cndmask_b32_e64 v48, v25, v19, s[44:45]
	v_cndmask_b32_e64 v19, v19, v25, s[44:45]
	v_cndmask_b32_e64 v25, v43, v21, s[44:45]
	v_cndmask_b32_e64 v21, v21, v43, s[44:45]
	v_add_f32_dpp v19, v19, v48 row_half_mirror row_mask:0xf bank_mask:0xf bound_ctrl:1
	s_nop 0
	v_add_f32_dpp v21, v21, v25 row_half_mirror row_mask:0xf bank_mask:0xf bound_ctrl:1
	v_cndmask_b32_e64 v25, v45, v23, s[44:45]
	v_cndmask_b32_e64 v23, v23, v45, s[44:45]
	s_nop 1
	v_add_f32_dpp v23, v23, v25 row_half_mirror row_mask:0xf bank_mask:0xf bound_ctrl:1
	v_cndmask_b32_e64 v25, v22, v24, s[44:45]
	v_cndmask_b32_e64 v22, v24, v22, s[44:45]
	v_cndmask_b32_e64 v24, v23, v19, s[46:47]
	v_cndmask_b32_e64 v19, v19, v23, s[46:47]
	v_add_f32_dpp v22, v22, v25 row_half_mirror row_mask:0xf bank_mask:0xf bound_ctrl:1
	s_nop 0
	v_add_f32_dpp v23, v19, v24 quad_perm:[2,3,0,1] row_mask:0xf bank_mask:0xf bound_ctrl:1
	v_cndmask_b32_e64 v19, v22, v21, s[46:47]
	v_cndmask_b32_e64 v21, v21, v22, s[46:47]
	s_nop 1
	v_add_f32_dpp v21, v21, v19 quad_perm:[2,3,0,1] row_mask:0xf bank_mask:0xf bound_ctrl:1
	v_cndmask_b32_e64 v19, v21, v23, s[48:49]
	v_cndmask_b32_e64 v22, v23, v21, s[48:49]
	v_mov_b32_e32 v21, v1
	s_nop 1
	v_mov_b32_dpp v21, v22 quad_perm:[1,0,3,2] row_mask:0xf bank_mask:0xf
	s_andn2_saveexec_b64 s[12:13], s[12:13]
	s_cbranch_execnz .LBB0_240
	s_branch .LBB0_241

; __device__ __forceinline__ unsigned cvt_pk_bf16(float lo, float hi) { unsigned r; asm volatile("v_cvt_pk_bf16_f32 %0, %1, %2" : "=v"(r) : "v"(lo), "v"(hi)); return r; }
; #define SCAN_COMMIT(bi) do { _Pragma("unroll") for (int j = 0; j < 3; ++j) { if (j < 2 || v2ok) { \
;             if (isW) st8n(bufW + ((bi) * TC + ps[j]) * SCW + pp[j] * 8, pre[j]); else st8n(bufG + ((bi) * TC + ps[j]) * SCG + pp[j] * 8, pre[j]); } } } while (0)
; __device__ __forceinline__ void scan_phase(const Args& a, int e, LAS unsigned char* lds) {
;     ...
;             obase[(size_t)c * TC * 1024] = (bf16)(cvt_pk_bf16(isW ? oacc : oacc * 0.125f, 0.f) & 0xffffu);
;             if (c + 1 < nc) SCAN_COMMIT(bi ^ 1);
;             __syncthreads();
;         }
.LBB0_241:
	s_or_b64 exec, exec, s[12:13]
	v_add_f32_e32 v19, v19, v21
	v_mul_f32_e32 v21, 0x3e000000, v19
	v_cndmask_b32_e64 v19, v21, v19, s[38:39]
	s_andn2_b64 vcc, exec, vcc
	v_cvt_pk_bf16_f32 v19, v19, v1
	global_store_short v[46:47], v19, off
.LBB0_245:
	s_mov_b64 s[12:13], 0x8000
	s_cmp_eq_u32 s10, s11
	v_lshl_add_u64 v[46:47], v[46:47], 0, s[12:13]
	s_waitcnt lgkmcnt(0)
	s_barrier
	s_cbranch_scc1 .LBB0_247
	s_mov_b32 s14, s11
	s_branch .LBB0_233
